# split-phase grid barrier after the layer-0 down-projection context-row fix-up: fix-up rows on workgroups 128..255, remaining layer-1 gate/up bias groups on 48..127, four-unit workgroups 0..47 go strai
# speedup vs baseline: 1.0186x; 1.0104x over previous
.Lxb7_rel:
.Lxb7_done:
.LBB0_906:
	s_or_b64 exec, exec, s[4:5]
	s_mov_b32 s1, 0
	s_waitcnt lgkmcnt(0)
	s_barrier
	s_load_dwordx2 s[4:5], s[82:83], 0xb0
	s_load_dwordx2 s[12:13], s[82:83], 0xa8
	s_mov_b32 s99, 0
	s_mov_b32 s94, s90
	s_mov_b32 s96, s88
	s_andn2_b64 vcc, exec, s[8:9]
	s_cmp_lg_u32 s70, 0x100
	s_cbranch_scc1 .Lp8_gen
	s_add_i32 s94, s90, 0xfffffc00
	s_movk_i32 s96, 0x400
	s_cmp_lt_i32 s94, 0
	s_cselect_b64 vcc, -1, 0
.Lp8_gen:
	s_mov_b32 s0, 0
	s_cbranch_vccnz .LBB0_911
	v_mbcnt_lo_u32_b32 v0, -1, s1
	v_mbcnt_hi_u32_b32 v0, -1, v0
	v_lshlrev_b32_e32 v4, 2, v0
	v_ashrrev_i32_e32 v5, 31, v4
	v_lshlrev_b64 v[6:7], 2, v[4:5]
	s_waitcnt lgkmcnt(0)
	v_lshl_add_u64 v[2:3], s[4:5], 0, v[6:7]
	s_mov_b64 s[8:9], 0x2d000
	v_cmp_eq_u32_e64 s[6:7], 0, v0
	v_lshl_add_u64 v[0:1], v[2:3], 0, s[8:9]
	s_mov_b64 s[8:9], 0x69000
	s_ashr_i32 s95, s94, 31
	v_lshl_add_u64 v[2:3], v[2:3], 0, s[8:9]
	s_lshl_b64 s[8:9], s[94:95], 2
	s_add_u32 s1, s8, 0x91000
	s_addc_u32 s2, s9, 0
	s_ashr_i32 s97, s96, 31
	s_lshl_b64 s[10:11], s[94:95], 11
	v_xor_b32_e32 v40, 0x80, v4
	s_lshl_b64 s[8:9], s[96:97], 2
	v_lshl_add_u64 v[4:5], v[4:5], 1, s[10:11]
	s_lshl_b64 s[10:11], s[96:97], 11
	s_lshl_b64 s[14:15], s[94:95], 12
	s_add_u32 s12, s12, s14
	s_addc_u32 s13, s13, s15
	v_lshl_add_u64 v[6:7], s[12:13], 0, v[6:7]
	s_lshl_b64 s[12:13], s[96:97], 12
	s_mov_b32 s16, 0x5000000
	s_mov_b32 s17, 0x9400000
	v_mov_b32_e32 v41, 0
	s_mov_b32 s18, s94
	s_branch .LBB0_909
.LBB0_908:
	s_or_b64 exec, exec, s[14:15]
	s_add_i32 s18, s18, s96
	s_add_u32 s1, s1, s8
	s_addc_u32 s2, s2, s9
	v_lshl_add_u64 v[4:5], v[4:5], 0, s[10:11]
	s_cmpk_lt_i32 s18, 0x400
	v_lshl_add_u64 v[6:7], v[6:7], 0, s[12:13]
	s_cbranch_scc0 .LBB0_911

.LBB0_917:
	s_mov_b32 s95, s90
	s_mov_b32 s96, s70
	s_cmp_lg_u32 s70, 0x100
	s_cbranch_scc1 .Lb8_norot
	s_add_i32 s95, s90, 0xfffffe80
	s_cmp_lt_u32 s95, 0x280
	s_cselect_b32 s95, s95, 0x7fff
	s_movk_i32 s96, 0x50

.LBB0_940:
	s_waitcnt lgkmcnt(0)
	v_readfirstlane_b32 s1, v2
	v_readfirstlane_b32 s10, v0
	s_lshl_b32 s0, s0, 8
	s_add_u32 s8, s6, s0
	s_addc_u32 s9, s7, 0
	v_mov_b32_e32 v3, 0x1000
	v_mov_b32_e32 v4, 1
	v_mov_b32_e32 v0, 0x2000
	global_atomic_add v3, v3, v4, s[8:9] offset:1024 sc0
	s_mul_i32 s1, s1, 9
	s_mul_i32 s10, s10, 9
	s_mov_b32 s13, 0
	s_waitcnt vmcnt(0)
	v_readfirstlane_b32 s11, v3
	s_add_u32 s11, s11, 1
	s_cmp_lg_u32 s11, s1
	s_cbranch_scc1 .Lxb8_wait
	buffer_wbl2 sc1
	buffer_inv sc1
	s_waitcnt vmcnt(0)
	v_mov_b32_e32 v3, 0x3000
	global_atomic_add v3, v3, v4, s[6:7] offset:1024 sc0
	s_waitcnt vmcnt(0)
	v_readfirstlane_b32 s11, v3
	s_add_u32 s11, s11, 1
	s_cmp_lg_u32 s11, s10
	s_cbranch_scc1 .Lxb8_poll
	v_mov_b32_e32 v5, 0x3000
	global_atomic_add v0, v4, s[6:7] offset:1024
	global_atomic_add v0, v4, s[6:7] offset:1280
	global_atomic_add v0, v4, s[6:7] offset:1536
	global_atomic_add v0, v4, s[6:7] offset:1792
	global_atomic_add v0, v4, s[6:7] offset:2048
	global_atomic_add v0, v4, s[6:7] offset:2304
	global_atomic_add v0, v4, s[6:7] offset:2560
	global_atomic_add v0, v4, s[6:7] offset:2816
	global_atomic_add v0, v4, s[6:7] offset:3072
	global_atomic_add v0, v4, s[6:7] offset:3328
	global_atomic_add v0, v4, s[6:7] offset:3584
	global_atomic_add v0, v4, s[6:7] offset:3840
	global_atomic_add v5, v4, s[6:7]
	global_atomic_add v5, v4, s[6:7] offset:256
	global_atomic_add v5, v4, s[6:7] offset:512
	global_atomic_add v5, v4, s[6:7] offset:768
	s_waitcnt vmcnt(0)
	s_branch .Lxb8_done
.Lxb8_wait:
	buffer_inv sc1
	s_waitcnt vmcnt(0)
	s_branch .Lxb8_done
	buffer_inv sc1
.Lxb8_poll:
	s_branch .Lxb8_done
	global_load_dword v1, v0, s[8:9] offset:1024 sc1
	s_add_u32 s13, s13, 1
	s_waitcnt vmcnt(0)
	v_readfirstlane_b32 s12, v1
	s_cmp_lg_u32 s12, 8
	s_cbranch_scc1 .Lxb8_rel
	s_cmp_lt_u32 s13, 0x40000
	s_cbranch_scc0 .Lxb8_rel
	s_sleep 1
	s_branch .Lxb8_poll

.LBB0_982:
	s_add_i32 s45, s45, 1
	s_mul_i32 s1, s75, s45
	s_mul_hi_u32 s6, s74, s45
	s_add_i32 s6, s6, s1
	s_mul_i32 s1, s74, s45
	s_add_u32 s22, s1, s93
	s_addc_u32 s23, s6, s73
	v_cmp_gt_i64_e32 vcc, s[22:23], v[158:159]
	v_cmp_lt_i64_e64 s[6:7], s[22:23], v[156:157]
	s_cbranch_vccnz .LBB0_984
	s_ashr_i32 s1, s22, 31
	s_lshr_b32 s1, s1, 29
	s_add_i32 s1, s22, s1
	s_ashr_i32 s18, s1, 3
	s_and_b32 s1, s1, -8
	s_sub_i32 s1, s22, s1
	s_cmp_lt_i32 s1, 0
	s_cselect_b32 s19, s41, 0x66
	s_mul_i32 s1, s1, s19
	s_add_i32 s1, s1, s18
	s_cmp_lt_u32 s1, 0x300
	s_cbranch_scc1 .Ldw9a_skip
	s_cmp_eq_u32 s99, 1
	s_cbranch_scc1 .Ldw9a_skip
	s_mov_b32 s99, 1
	s_load_dwordx2 s[60:61], s[82:83], 0xb0
	s_getreg_b32 s98, hwreg(HW_REG_XCC_ID, 0, 4)
	s_and_b32 s98, s98, 15
	s_lshl_b32 s98, s98, 8
	s_add_i32 s98, s98, 0x2400
	v_mov_b32_e32 v229, s98
	s_mov_b32 s100, 0
	s_waitcnt lgkmcnt(0)
.Ldw9a_poll:
	global_load_dword v230, v229, s[60:61] sc1
	s_waitcnt vmcnt(0)
	v_readfirstlane_b32 s101, v230
	s_cmp_lg_u32 s101, 8
	s_cbranch_scc1 .Ldw9a_skip
	s_add_u32 s100, s100, 1
	s_cmp_lt_u32 s100, 0x40000
	s_cbranch_scc0 .Ldw9a_skip
	s_sleep 1
	s_branch .Ldw9a_poll
.Ldw9a_skip:
	s_mul_hi_i32 s18, s1, 0x2aaaaaab
	s_lshr_b32 s19, s18, 31
	s_ashr_i32 s18, s18, 3
	s_add_i32 s18, s18, s19
	s_lshl_b32 s19, s18, 2
	s_sub_i32 s20, 0x44, s19
	s_min_i32 s20, s20, 4
	s_abs_i32 s21, s20
	v_cvt_f32_u32_e32 v0, s21
	s_sub_i32 s23, 0, s21
	s_mul_i32 s18, s18, 48
	s_sub_i32 s1, s1, s18
	v_rcp_iflag_f32_e32 v0, v0
	s_abs_i32 s18, s1
	s_xor_b32 s22, s1, s20
	s_ashr_i32 s22, s22, 31
	v_mul_f32_e32 v0, 0x4f7ffffe, v0
	v_cvt_u32_f32_e32 v0, v0
	s_nop 0
	v_readfirstlane_b32 s24, v0
	s_mul_i32 s23, s23, s24
	s_mul_hi_u32 s23, s24, s23
	s_add_i32 s24, s24, s23
	s_mul_hi_u32 s23, s18, s24
	s_mul_i32 s24, s23, s21
	s_sub_i32 s18, s18, s24
	s_add_i32 s25, s23, 1
	s_sub_i32 s24, s18, s21
	s_cmp_ge_u32 s18, s21
	s_cselect_b32 s23, s25, s23
	s_cselect_b32 s18, s24, s18
	s_add_i32 s24, s23, 1
	s_cmp_ge_u32 s18, s21
	s_cselect_b32 s18, s24, s23
	s_xor_b32 s18, s18, s22
	s_sub_i32 s18, s18, s22
	s_mul_i32 s20, s18, s20
	s_sub_i32 s1, s1, s20
	s_add_i32 s20, s19, s1

.LBB0_992:
	s_mov_b32 s0, 0
	s_movk_i32 s6, 0x210
	v_mbcnt_lo_u32_b32 v0, -1, s0
	v_mbcnt_hi_u32_b32 v1, -1, v0
	v_readlane_b32 s0, v254, 7
	v_and_b32_e32 v6, 31, v1
	v_and_b32_e32 v12, 7, v1
	v_add_u32_e32 v3, s0, v1
	v_bfe_u32 v15, v3, 6, 1
	v_lshlrev_b32_e32 v4, 5, v1
	v_bfe_u32 v14, v3, 7, 1
	v_lshl_or_b32 v6, v15, 5, v6
	v_lshrrev_b32_e32 v1, 2, v1
	v_mad_u32_u24 v6, v6, s6, 0
	v_lshlrev_b32_e32 v7, 5, v14
	v_and_b32_e32 v1, 8, v1
	v_ashrrev_i32_e32 v87, 3, v3
	v_add_u32_e32 v16, 0x200, v3
	v_and_b32_e32 v5, 0xc0, v4
	v_and_b32_e32 v4, 32, v4
	v_add3_u32 v1, v6, v7, v1
	v_ashrrev_i32_e32 v88, 3, v16
	v_add_u32_e32 v17, 0x400, v3
	v_and_b32_e32 v6, 31, v87
	v_ashrrev_i32_e32 v89, 3, v17
	v_add_u32_e32 v18, 0x600, v3
	v_or3_b32 v19, v6, v5, v4
	v_and_b32_e32 v6, 31, v88
	v_ashrrev_i32_e32 v90, 3, v18
	v_or3_b32 v20, v5, v6, v4
	v_and_b32_e32 v6, 31, v89
	v_or3_b32 v21, v5, v6, v4
	v_and_b32_e32 v6, 31, v90
	v_or3_b32 v22, v5, v6, v4
	v_ashrrev_i32_e32 v4, 5, v3
	s_load_dwordx2 s[4:5], s[82:83], 0xa8
	v_and_b32_e32 v4, -8, v4
	v_ashrrev_i32_e32 v6, 5, v16
	v_ashrrev_i32_e32 v8, 5, v17
	v_ashrrev_i32_e32 v10, 5, v18
	v_ashrrev_i32_e32 v5, 31, v4
	v_and_b32_e32 v6, -8, v6
	v_and_b32_e32 v8, -8, v8
	v_and_b32_e32 v10, -8, v10
	v_ashrrev_i32_e32 v7, 31, v6
	v_mul_lo_u32 v23, v4, s6
	v_mul_lo_u32 v48, v6, s6
	v_mul_lo_u32 v49, v8, s6
	v_mul_lo_u32 v50, v10, s6
	s_waitcnt lgkmcnt(0)
	v_lshl_add_u64 v[4:5], v[4:5], 1, s[8:9]
	s_mov_b64 s[6:7], 0x9600000
	s_add_u32 s0, s8, 0x100000
	v_ashrrev_i32_e32 v9, 31, v8
	v_lshl_add_u64 v[36:37], v[4:5], 0, s[6:7]
	v_lshl_add_u64 v[4:5], v[6:7], 1, s[8:9]
	s_addc_u32 s1, s9, 0
	v_lshlrev_b32_e32 v2, 3, v3
	v_and_b32_e32 v86, 0xff, v3
	v_ashrrev_i32_e32 v11, 31, v10
	v_ashrrev_i32_e32 v91, 8, v3
	v_lshl_add_u64 v[38:39], v[4:5], 0, s[6:7]
	v_lshl_add_u64 v[4:5], v[8:9], 1, s[8:9]
	v_and_b32_e32 v3, 7, v3
	s_add_u32 s2, s4, 0x2000000
	v_mov_b32_e32 v25, 0
	v_lshl_add_u64 v[40:41], v[4:5], 0, s[6:7]
	v_lshl_add_u64 v[4:5], v[10:11], 1, s[8:9]
	v_lshlrev_b32_e32 v24, 4, v3
	s_addc_u32 s20, s5, 0
	v_lshlrev_b32_e32 v15, 10, v15
	v_ashrrev_i32_e32 v92, 8, v16
	v_ashrrev_i32_e32 v93, 8, v17
	v_ashrrev_i32_e32 v94, 8, v18
	v_lshl_add_u64 v[42:43], v[4:5], 0, s[6:7]
	v_lshl_add_u64 v[4:5], s[8:9], 0, v[24:25]
	v_lshlrev_b32_e32 v24, 4, v12
	s_add_u32 s21, s8, 0x300000
	v_and_b32_e32 v0, 56, v2
	v_lshl_add_u32 v13, v86, 1, 0
	v_and_b32_e32 v2, 0x1f8, v2
	v_lshlrev_b32_e32 v51, 6, v91
	v_lshl_or_b32 v26, v14, 11, v15
	v_lshlrev_b32_e32 v14, 6, v92
	v_lshlrev_b32_e32 v15, 6, v93
	v_lshlrev_b32_e32 v16, 6, v94
	v_lshl_add_u64 v[44:45], v[4:5], 0, s[6:7]
	v_lshl_add_u64 v[4:5], s[8:9], 0, v[24:25]
	s_addc_u32 s22, s9, 0
	v_mov_b32_e32 v27, v25
	v_lshlrev_b32_e32 v28, 4, v19
	v_mov_b32_e32 v29, v25
	v_lshlrev_b32_e32 v30, 4, v20
	v_mov_b32_e32 v31, v25
	v_lshlrev_b32_e32 v32, 4, v21
	v_mov_b32_e32 v33, v25
	v_lshlrev_b32_e32 v34, 4, v22
	v_mov_b32_e32 v35, v25
	v_lshl_add_u64 v[46:47], v[4:5], 0, s[6:7]
	s_movk_i32 s23, 0x67
	v_lshlrev_b32_e32 v24, 1, v2
	s_movk_i32 s24, 0x1800
	v_lshlrev_b32_e32 v95, 2, v0
	v_mov_b32_e32 v96, 0x358637bd
	v_add_u32_e32 v97, v13, v23
	v_add_u32_e32 v98, v13, v48
	v_add_u32_e32 v99, v13, v49
	v_add_u32_e32 v100, v13, v50
	v_add_u32_e32 v101, v1, v51
	v_add_u32_e32 v102, v1, v14
	v_add_u32_e32 v103, v1, v15
	v_add_u32_e32 v104, v1, v16
	v_mov_b64_e32 v[48:49], 0x32f
	v_mov_b64_e32 v[50:51], 0x330
	v_mov_b32_e32 v105, 0x3e38aa3b
	s_cmp_eq_u32 s99, 1
	s_cbranch_scc1 .Ldw9b_skip
	s_mov_b32 s99, 1
	s_load_dwordx2 s[60:61], s[82:83], 0xb0
	s_getreg_b32 s98, hwreg(HW_REG_XCC_ID, 0, 4)
	s_and_b32 s98, s98, 15
	s_lshl_b32 s98, s98, 8
	s_add_i32 s98, s98, 0x2400
	v_mov_b32_e32 v229, s98
	s_mov_b32 s100, 0
	s_waitcnt lgkmcnt(0)

.Ldw9b_skip:
	s_cmp_lg_u32 s74, 0x100
	s_cbranch_scc1 .Lps_generic
	s_cmp_lg_u32 s75, 0
	s_cbranch_scc1 .Lps_generic
	s_mov_b32 s94, s93
	s_mov_b32 s95, -1
	s_getreg_b32 s96, hwreg(HW_REG_XCC_ID, 0, 4)
	s_and_b32 s96, s96, 15
	s_load_dwordx2 s[40:41], s[82:83], 0xb0
	s_mov_b64 s[38:39], 0
	s_and_b64 vcc, exec, s[86:87]
	s_cbranch_vccz .Lps_nolead
	v_mbcnt_lo_u32_b32 v122, -1, 0
	v_mbcnt_hi_u32_b32 v122, -1, v122
	v_cmp_eq_u32_e32 vcc, 0, v122
	s_and_b64 s[38:39], vcc, exec

.LBB0_1044:
	s_waitcnt lgkmcnt(0)
	v_readfirstlane_b32 s1, v2
	v_readfirstlane_b32 s10, v0
	s_lshl_b32 s0, s0, 8
	s_add_u32 s8, s6, s0
	s_addc_u32 s9, s7, 0
	v_mov_b32_e32 v3, 0x1000
	v_mov_b32_e32 v4, 1
	v_mov_b32_e32 v0, 0x2000
	s_mov_b32 s11, 0
.Lxb9_prepoll:
	global_load_dword v1, v0, s[8:9] offset:1024 sc1
	s_add_u32 s11, s11, 1
	s_waitcnt vmcnt(0)
	v_readfirstlane_b32 s12, v1
	s_cmp_lg_u32 s12, 8
	s_cbranch_scc1 .Lxb9_preok
	s_cmp_lt_u32 s11, 0x40000
	s_cbranch_scc0 .Lxb9_preok
	s_sleep 1
	s_branch .Lxb9_prepoll
.Lxb9_preok:
	global_atomic_add v3, v3, v4, s[8:9] offset:1024 sc0
	s_mul_i32 s1, s1, 10
	s_mul_i32 s10, s10, 10
	s_mov_b32 s13, 0
	s_waitcnt vmcnt(0)
	v_readfirstlane_b32 s11, v3
	s_add_u32 s11, s11, 1
	s_cmp_lg_u32 s11, s1
	s_cbranch_scc1 .Lxb9_wait
	buffer_wbl2 sc1
	buffer_inv sc1
	s_waitcnt vmcnt(0)
	v_mov_b32_e32 v3, 0x3000
	global_atomic_add v3, v3, v4, s[6:7] offset:1024 sc0
	s_waitcnt vmcnt(0)
	v_readfirstlane_b32 s11, v3
	s_add_u32 s11, s11, 1
	s_cmp_lg_u32 s11, s10
	s_cbranch_scc1 .Lxb9_poll
	v_mov_b32_e32 v5, 0x3000
	global_atomic_add v0, v4, s[6:7] offset:1024
	global_atomic_add v0, v4, s[6:7] offset:1280
	global_atomic_add v0, v4, s[6:7] offset:1536
	global_atomic_add v0, v4, s[6:7] offset:1792
	global_atomic_add v0, v4, s[6:7] offset:2048
	global_atomic_add v0, v4, s[6:7] offset:2304
	global_atomic_add v0, v4, s[6:7] offset:2560
	global_atomic_add v0, v4, s[6:7] offset:2816
	global_atomic_add v0, v4, s[6:7] offset:3072
	global_atomic_add v0, v4, s[6:7] offset:3328
	global_atomic_add v0, v4, s[6:7] offset:3584
	global_atomic_add v0, v4, s[6:7] offset:3840
	global_atomic_add v5, v4, s[6:7]
	global_atomic_add v5, v4, s[6:7] offset:256
	global_atomic_add v5, v4, s[6:7] offset:512
	global_atomic_add v5, v4, s[6:7] offset:768
	s_waitcnt vmcnt(0)
	s_branch .Lxb9_done
